# P4 (W_o + residual) epilogue: one-dword prefetch touches of all 8 row-blocks' x rows issued at epilogue start so the 16 serialised HBM round trips hit L2
# baseline (speedup 1.0000x reference)
;     __device__ __forceinline__ void operator()(const pg8::f32x4 (&acc)[2][2][4][2], const Unit& u, int wr, int wc, int fr, int fq) const {
;     ...
;         for (int ai = 0; ai < 2; ++ai)
; #pragma unroll
;             for (int m = 0; m < 4; ++m) { const int row = rbase + ai * 128 + m * 16;
;                 const float* xin = row < ROW_S0 ? c.x_prompt + (size_t)row * D : c.x_sample + (size_t)(row - ROW_S0) * D;
;                 float s = 0.f;
; #pragma unroll
;                 for (int bj = 0; bj < 2; ++bj) { const int col = cl + bj * 128; f32x4 v0, v1;
;                     if (WHICH == 0) { v0 = acc[ai][bj][m][0] + __builtin_nontemporal_load((const f32x4*)(xin + col)); v1 = acc[ai][bj][m][1] + __builtin_nontemporal_load((const f32x4*)(xin + col + 4));
;                         *(u32x4*)(HB + (size_t)row * D + col) = pack8(v0, v1); }
;                     else { float hf[8]; unpack8(*(const u32x4*)(HB + (size_t)row * D + col), hf);
; #pragma unroll
;                         for (int j = 0; j < 4; ++j) { v0[j] = acc[ai][bj][m][0][j] + hf[j]; v1[j] = acc[ai][bj][m][1][j] + hf[4 + j]; }
;                         *(u32x4*)(H2 + (size_t)row * D + col) = pack8(v0, v1); }
;                     s += (v0[0] * v0[0] + v0[1] * v0[1]) + (v0[2] * v0[2] + v0[3] * v0[3]) + (v1[0] * v1[0] + v1[1] * v1[1]) + (v1[2] * v1[2] + v1[3] * v1[3]); }
;                 s += __shfl_xor(s, 16); s += __shfl_xor(s, 32);
;                 if (fq == 0) SS[(size_t)row * 16 + u.pn * 4 + wc] = s; }
.LBB0_1141:
	v_lshl_add_u32 v148, s40, 8, v152
	v_cmp_lt_i32_e32 vcc, s68, v148
	s_and_saveexec_b64 s[40:41], vcc
	s_xor_b64 s[40:41], exec, s[40:41]
	v_add_u32_e32 v136, 0xffff8000, v148
	v_lshlrev_b64 v[146:147], 12, v[136:137]
	v_lshl_add_u64 v[150:151], s[38:39], 0, v[146:147]
	v_mov_b32_e32 v149, v137
	s_andn2_saveexec_b64 s[40:41], s[40:41]
	v_ashrrev_i32_e32 v149, 31, v148
	v_lshlrev_b64 v[146:147], 12, v[148:149]
	v_lshl_add_u64 v[150:151], s[36:37], 0, v[146:147]
	s_or_b64 exec, exec, s[40:41]
	v_lshl_or_b32 v146, s26, 8, v154
	v_ashrrev_i32_e32 v147, 31, v146
	v_lshl_add_u64 v[150:151], v[146:147], 2, v[150:151]
	s_mov_b32 s98, 0x10000
	s_mov_b32 s99, 0
	v_lshl_add_u64 v[230:231], v[150:151], 0, s[98:99]
	global_load_dword v232, v[230:231], off
	global_load_dword v233, v[230:231], off offset:512
	v_lshl_add_u64 v[230:231], v[230:231], 0, s[98:99]
	global_load_dword v234, v[230:231], off
	global_load_dword v235, v[230:231], off offset:512
	v_lshl_add_u64 v[230:231], v[230:231], 0, s[98:99]
	global_load_dword v236, v[230:231], off
	global_load_dword v237, v[230:231], off offset:512
	s_mov_b32 s98, 0x50000
	v_lshl_add_u64 v[230:231], v[230:231], 0, s[98:99]
	global_load_dword v238, v[230:231], off
	global_load_dword v239, v[230:231], off offset:512
	s_mov_b32 s98, 0x10000
	v_lshl_add_u64 v[230:231], v[230:231], 0, s[98:99]
	global_load_dword v240, v[230:231], off
	global_load_dword v241, v[230:231], off offset:512
	v_lshl_add_u64 v[230:231], v[230:231], 0, s[98:99]
	global_load_dword v242, v[230:231], off
	global_load_dword v243, v[230:231], off offset:512
	v_lshl_add_u64 v[230:231], v[230:231], 0, s[98:99]
	global_load_dword v244, v[230:231], off
	global_load_dword v245, v[230:231], off offset:512
	global_load_dword v246, v[150:151], off offset:512
	global_load_dwordx4 v[158:161], v[150:151], off nt
	global_load_dwordx4 v[162:165], v[150:151], off offset:16 nt
	v_lshlrev_b64 v[166:167], 11, v[148:149]
	v_lshl_add_u64 v[166:167], s[28:29], 0, v[166:167]
	v_lshl_add_u64 v[166:167], v[146:147], 1, v[166:167]
	v_xor_b32_e32 v136, 32, v212
	s_lshl_b32 s26, s26, 2
	s_ashr_i32 s27, s26, 31
	s_lshl_b64 s[26:27], s[26:27], 2
	s_add_u32 s26, s64, s26
	s_addc_u32 s27, s65, s27
	s_waitcnt vmcnt(0)
	v_pk_add_f32 v[126:127], v[126:127], v[160:161]
	v_pk_add_f32 v[168:169], v[124:125], v[158:159]
	v_pk_add_f32 v[164:165], v[122:123], v[164:165]
	v_pk_add_f32 v[162:163], v[120:121], v[162:163]
	v_cvt_pk_bf16_f32 v120, v168, v169
	v_cvt_pk_bf16_f32 v121, v126, v127
	v_mul_f32_e32 v127, v127, v127
	v_cvt_pk_bf16_f32 v122, v162, v163
	v_cvt_pk_bf16_f32 v123, v164, v165
	global_store_dwordx4 v[166:167], v[120:123], off
	global_load_dwordx4 v[122:125], v[150:151], off offset:512 nt
	s_nop 0
	global_load_dwordx4 v[158:161], v[150:151], off offset:528 nt
	v_mul_f32_e32 v150, v169, v169
	v_and_b32_e32 v121, 64, v212
	v_mul_f32_e32 v151, v163, v163
	v_fmac_f32_e32 v150, v168, v168
	v_fmac_f32_e32 v127, v126, v126
	v_xor_b32_e32 v120, 16, v212
	v_add_u32_e32 v121, 64, v121
	v_mul_f32_e32 v163, v165, v165
	v_fmac_f32_e32 v151, v162, v162
	v_add_f32_e32 v126, v150, v127
	v_cmp_lt_i32_e32 vcc, v120, v121
	v_fmac_f32_e32 v163, v164, v164
	v_add_f32_e32 v126, v126, v151
	v_cndmask_b32_e32 v120, v212, v120, vcc
	v_add_f32_e32 v126, v163, v126
	v_lshlrev_b32_e32 v120, 2, v120
	v_cmp_lt_i32_e32 vcc, v136, v121
	s_waitcnt vmcnt(1)
	v_pk_add_f32 v[118:119], v[118:119], v[124:125]
	v_pk_add_f32 v[116:117], v[116:117], v[122:123]
	s_waitcnt vmcnt(0)
	v_pk_add_f32 v[124:125], v[112:113], v[158:159]
	v_mul_f32_e32 v112, v117, v117
	v_mul_f32_e32 v113, v119, v119
	v_pk_add_f32 v[114:115], v[114:115], v[160:161]
	v_mul_f32_e32 v122, v125, v125
	v_fmac_f32_e32 v112, v116, v116
	v_fmac_f32_e32 v113, v118, v118
	v_mul_f32_e32 v123, v115, v115
	v_fmac_f32_e32 v122, v124, v124
	v_add_f32_e32 v112, v112, v113
	v_fmac_f32_e32 v123, v114, v114
	v_add_f32_e32 v112, v112, v122
	v_add_f32_e32 v112, v123, v112
	v_add_f32_e32 v112, v126, v112
	ds_bpermute_b32 v113, v120, v112
	v_cndmask_b32_e32 v121, v212, v136, vcc
	v_cvt_pk_bf16_f32 v122, v116, v117
	v_lshlrev_b32_e32 v116, 2, v121
	v_cvt_pk_bf16_f32 v123, v118, v119
	s_waitcnt lgkmcnt(0)
	v_add_f32_e32 v112, v112, v113
	ds_bpermute_b32 v113, v116, v112
	v_cvt_pk_bf16_f32 v124, v124, v125
	v_cvt_pk_bf16_f32 v125, v114, v115
	global_store_dwordx4 v[166:167], v[122:125], off offset:256
	s_and_saveexec_b64 s[40:41], s[2:3]
	s_cbranch_execz .LBB0_1147
	s_waitcnt lgkmcnt(0)
	v_add_f32_e32 v114, v112, v113
	v_lshlrev_b64 v[112:113], 6, v[148:149]
	v_lshl_add_u64 v[112:113], s[26:27], 0, v[112:113]
	global_store_dword v[112:113], v114, off
